# RG-LRU pass 3 gate front: 16 weight loads + nt0 biases in one batch (was 5 serialized batches), other biases behind the MFMAs
# speedup vs baseline: 1.0490x; 1.0099x over previous
.LBB0_355:
	s_or_b64 exec, exec, s[8:9]
	v_mov_b32_e32 v161, v191
	s_waitcnt lgkmcnt(0)
	s_barrier
	v_mov_b32_e32 v162, v191
	v_and_b32_e32 v168, 15, v161
	v_lshrrev_b32_e32 v169, 4, v161
	v_bfe_u32 v170, v161, 4, 2
	s_mov_b64 s[2:3], s[74:75]
	v_bfe_u32 v163, v161, 1, 3
	v_ashrrev_i32_e32 v141, 6, v161
	v_lshlrev_b32_e32 v142, 7, v168
	v_bitop3_b32 v8, v169, v163, 3 bitop3:0x6c
	v_bitop3_b32 v13, v170, v163, 4 bitop3:0x36
	v_lshl_or_b32 v12, v141, 11, v142
	v_lshlrev_b32_e32 v8, 4, v8
	v_lshlrev_b32_e32 v13, 4, v13
	s_add_u32 s2, s2, s29
	v_add3_u32 v8, s60, v8, v12
	v_add3_u32 v12, s60, v13, v12
	s_addc_u32 s3, s3, 0
	v_lshlrev_b32_e32 v144, 4, v170
	ds_read_b128 v[8:11], v8
	ds_read_b128 v[72:75], v12
	v_lshl_add_u64 v[12:13], s[2:3], 0, v[144:145]
	s_mov_b64 s[2:3], 0x3980000
	v_lshl_add_u64 v[164:165], v[12:13], 0, s[2:3]
	s_mov_b64 s[2:3], 0x39a0000
	v_mov_b32_e32 v143, v145
	v_lshl_add_u64 v[166:167], v[12:13], 0, s[2:3]
	v_mul_u32_u24_e32 v184, 0xf0, v170
	v_lshl_add_u32 v184, v168, 4, v184
	v_mov_b32_e32 v185, v145
	v_lshl_add_u64 v[60:61], v[164:165], 0, v[184:185]
	v_lshl_add_u64 v[62:63], v[166:167], 0, v[184:185]
	s_mov_b64 s[98:99], 0x1000
	v_lshl_add_u64 v[174:175], v[60:61], 0, s[98:99]
	v_lshl_add_u64 v[176:177], v[62:63], 0, s[98:99]
	v_lshrrev_b32_e32 v172, 1, v161
	v_readlane_b32 s40, v254, 22
	v_readlane_b32 s44, v254, 26
	v_readlane_b32 s45, v254, 27
	s_mov_b64 s[2:3], s[44:45]
	v_readlane_b32 s48, v254, 30
	v_readlane_b32 s49, v254, 31
	s_mov_b64 s[8:9], s[48:49]
	s_mov_b32 s37, 0x122e6000
	s_mov_b32 s38, 0xc1000000
	v_readlane_b32 s41, v254, 23
	v_readlane_b32 s42, v254, 24
	v_readlane_b32 s43, v254, 25
	v_readlane_b32 s46, v254, 28
	v_readlane_b32 s47, v254, 29
	v_readlane_b32 s50, v254, 32
	v_readlane_b32 s51, v254, 33
	v_readlane_b32 s52, v254, 34
	v_readlane_b32 s53, v254, 35
	v_readlane_b32 s54, v254, 36
	v_readlane_b32 s55, v254, 37
	v_lshlrev_b32_e32 v142, 2, v170
	v_mov_b32_e32 v143, v145
	global_load_dwordx4 v[68:71], v[60:61], off
	global_load_dwordx4 v[64:67], v[62:63], off
	global_load_dwordx4 v[216:219], v[60:61], off offset:1024
	global_load_dwordx4 v[220:223], v[62:63], off offset:1024
	global_load_dwordx4 v[56:59], v[62:63], off offset:2048
	global_load_dwordx4 v[224:227], v[60:61], off offset:3072
	global_load_dwordx4 v[228:231], v[62:63], off offset:3072
	global_load_dwordx4 v[60:63], v[60:61], off offset:2048
	global_load_dwordx4 v[52:55], v[174:175], off
	global_load_dwordx4 v[48:51], v[176:177], off
	global_load_dwordx4 v[232:235], v[174:175], off offset:1024
	global_load_dwordx4 v[236:239], v[176:177], off offset:1024
	global_load_dwordx4 v[12:15], v[174:175], off offset:2048
	global_load_dwordx4 v[248:251], v[176:177], off offset:2048
	global_load_dwordx4 v[240:243], v[174:175], off offset:3072
	global_load_dwordx4 v[244:247], v[176:177], off offset:3072
	v_or_b32_e32 v146, s22, v142
	v_ashrrev_i32_e32 v147, 31, v146
	v_lshlrev_b64 v[146:147], 2, v[146:147]
	s_add_u32 s98, s74, s30
	s_addc_u32 s99, s75, 0
	s_add_u32 s98, s98, 0x122e6000
	s_addc_u32 s99, s99, 0
	v_lshl_add_u64 v[182:183], s[98:99], 0, v[144:145]
	v_lshl_add_u64 v[174:175], s[44:45], 0, v[146:147]
	v_lshl_add_u64 v[176:177], s[48:49], 0, v[146:147]
	global_load_dwordx4 v[146:149], v[174:175], off
	global_load_dwordx4 v[178:181], v[176:177], off
	global_load_dwordx4 v[182:185], v[182:183], off
	s_waitcnt vmcnt(0) lgkmcnt(0)
	v_mfma_f32_16x16x32_bf16 v[68:71], v[68:71], v[8:11], 0
	v_mfma_f32_16x16x32_bf16 v[64:67], v[64:67], v[8:11], 0
	v_mfma_f32_16x16x32_bf16 v[60:63], v[60:63], v[8:11], 0
	v_mfma_f32_16x16x32_bf16 v[56:59], v[56:59], v[8:11], 0
	v_mfma_f32_16x16x32_bf16 v[52:55], v[52:55], v[8:11], 0
	v_mfma_f32_16x16x32_bf16 v[48:51], v[48:51], v[8:11], 0
	v_mfma_f32_16x16x32_bf16 v[12:15], v[12:15], v[8:11], 0
	v_mfma_f32_16x16x32_bf16 v[8:11], v[248:251], v[8:11], 0
	v_mfma_f32_16x16x32_bf16 v[68:71], v[216:219], v[72:75], v[68:71]
	v_mfma_f32_16x16x32_bf16 v[64:67], v[220:223], v[72:75], v[64:67]
	v_mfma_f32_16x16x32_bf16 v[60:63], v[224:227], v[72:75], v[60:63]
	v_mfma_f32_16x16x32_bf16 v[56:59], v[228:231], v[72:75], v[56:59]
	v_mfma_f32_16x16x32_bf16 v[52:55], v[232:235], v[72:75], v[52:55]
	v_mfma_f32_16x16x32_bf16 v[48:51], v[236:239], v[72:75], v[48:51]
	v_mfma_f32_16x16x32_bf16 v[12:15], v[240:243], v[72:75], v[12:15]
	v_mfma_f32_16x16x32_bf16 v[8:11], v[244:247], v[72:75], v[8:11]
	v_lshl_add_u64 v[248:249], s[98:99], 0, v[144:145]
	global_load_dwordx4 v[216:219], v[174:175], off offset:64
	global_load_dwordx4 v[220:223], v[176:177], off offset:64
	global_load_dwordx4 v[224:227], v[248:249], off offset:64
	global_load_dwordx4 v[228:231], v[174:175], off offset:128
	global_load_dwordx4 v[232:235], v[176:177], off offset:128
	global_load_dwordx4 v[236:239], v[248:249], off offset:128
	global_load_dwordx4 v[240:243], v[174:175], off offset:192
	global_load_dwordx4 v[244:247], v[176:177], off offset:192
	global_load_dwordx4 v[248:251], v[248:249], off offset:192
	v_lshl_or_b32 v72, v141, 4, v168
	v_lshlrev_b32_e32 v164, 7, v72
	v_and_b32_e32 v73, 8, v172
	v_lshlrev_b32_e32 v167, 8, v72
	v_or_b32_e32 v72, s22, v142
	v_add_u32_e32 v166, s60, v73
	v_ashrrev_i32_e32 v73, 31, v72
	s_mov_b64 s[2:3], s[74:75]
	s_add_u32 s2, s2, s30
	s_addc_u32 s3, s3, 0
	v_bfe_u32 v165, v169, 1, 1
	v_lshl_add_u64 v[168:169], s[2:3], 0, v[144:145]
	v_add_co_u32_e64 v168, s[8:9], s37, v168
	v_bitop3_b32 v172, v165, v172, 7 bitop3:0x78
	s_nop 0
	v_addc_co_u32_e64 v169, s[8:9], 0, v169, s[8:9]
	v_lshlrev_b32_e32 v172, 4, v172
	v_add3_u32 v172, v166, v172, v164
	ds_read_b64 v[172:173], v172
	s_mov_b64 s[2:3], s[44:45]
	s_waitcnt lgkmcnt(0)
	v_lshlrev_b32_e32 v174, 16, v172
	v_and_b32_e32 v175, 0xffff0000, v172
	v_lshlrev_b32_e32 v172, 16, v173
	v_and_b32_e32 v173, 0xffff0000, v173
	v_add_f32_e32 v68, v68, v146
	v_add_f32_e32 v69, v69, v147
	v_mul_f32_e32 v68, 0xbfb8aa3b, v68
	v_mul_f32_e32 v69, 0xbfb8aa3b, v69
	v_exp_f32_e32 v68, v68
	v_exp_f32_e32 v69, v69
	v_add_f32_e32 v64, v64, v178
	v_add_f32_e32 v65, v65, v179
	v_add_f32_e32 v68, 1.0, v68
	v_add_f32_e32 v69, 1.0, v69
	v_rcp_f32_e32 v68, v68
	v_rcp_f32_e32 v69, v69
	v_add_f32_e32 v70, v70, v148
	v_add_f32_e32 v71, v71, v149
	v_mul_f32_e32 v70, 0xbfb8aa3b, v70
	v_pk_mul_f32 v[68:69], v[68:69], s[38:39] op_sel_hi:[1,0]
	v_mul_f32_e32 v71, 0xbfb8aa3b, v71
	v_pk_mul_f32 v[72:73], v[182:183], v[68:69]
	v_exp_f32_e32 v70, v70
	v_pk_add_f32 v[146:147], v[72:73], v[72:73]
	v_mul_f32_e32 v68, 0x3fb8aa3b, v72
	v_fmamk_f32 v69, v146, 0x3ab60b61, v195
	v_exp_f32_e32 v68, v68
	v_fmaak_f32 v69, v146, v69, 0x3d2aaaab
	v_fmaak_f32 v69, v146, v69, 0x3e2aaaab
	v_exp_f32_e32 v71, v71
	v_fma_f32 v69, v146, v69, 0.5
	v_fma_f32 v69, v146, v69, 1.0
	v_mul_f32_e64 v69, v69, -v146
	v_fma_f32 v72, -v68, v68, 1.0
	v_cmp_lt_f32_e64 s[12:13], s84, v146
	v_add_f32_e32 v70, 1.0, v70
	v_add_f32_e32 v71, 1.0, v71
	v_cndmask_b32_e64 v69, v72, v69, s[12:13]
	v_sqrt_f32_e32 v72, v69
	v_mul_f32_e32 v69, 0x3fb8aa3b, v73
	v_fmamk_f32 v73, v147, 0x3ab60b61, v195
	v_rcp_f32_e32 v70, v70
	v_rcp_f32_e32 v71, v71
	v_exp_f32_e32 v69, v69
	v_fmaak_f32 v73, v147, v73, 0x3d2aaaab
	v_fmaak_f32 v73, v147, v73, 0x3e2aaaab
	v_fma_f32 v73, v147, v73, 0.5
	v_fma_f32 v73, v147, v73, 1.0
	v_pk_mul_f32 v[70:71], v[70:71], s[38:39] op_sel_hi:[1,0]
	v_cmp_lt_f32_e64 s[8:9], s84, v147
	v_mul_f32_e64 v73, v73, -v147
	v_fma_f32 v146, -v69, v69, 1.0
	v_pk_mul_f32 v[74:75], v[184:185], v[70:71]
	v_cndmask_b32_e64 v73, v146, v73, s[8:9]
	v_pk_add_f32 v[146:147], v[74:75], v[74:75]
	v_mul_f32_e32 v70, 0x3fb8aa3b, v74
	v_fmamk_f32 v71, v146, 0x3ab60b61, v195
	v_exp_f32_e32 v70, v70
	v_fmaak_f32 v71, v146, v71, 0x3d2aaaab
	v_fmaak_f32 v71, v146, v71, 0x3e2aaaab
	v_fma_f32 v71, v146, v71, 0.5
	v_fma_f32 v71, v146, v71, 1.0
	v_mul_f32_e64 v71, v71, -v146
	v_fma_f32 v74, -v70, v70, 1.0
	v_cmp_lt_f32_e64 s[12:13], s84, v146
	v_add_f32_e32 v66, v66, v180
	v_add_f32_e32 v67, v67, v181
	v_cndmask_b32_e64 v71, v74, v71, s[12:13]
	v_sqrt_f32_e32 v74, v71
	v_mul_f32_e32 v71, 0x3fb8aa3b, v75
	v_fmamk_f32 v75, v147, 0x3ab60b61, v195
	v_mul_f32_e32 v64, 0xbfb8aa3b, v64
	v_mul_f32_e32 v65, 0xbfb8aa3b, v65
	v_mul_f32_e32 v66, 0xbfb8aa3b, v66
	v_mul_f32_e32 v67, 0xbfb8aa3b, v67
	v_exp_f32_e32 v71, v71
	v_fmaak_f32 v75, v147, v75, 0x3d2aaaab
	v_exp_f32_e32 v64, v64
	v_exp_f32_e32 v65, v65
	v_exp_f32_e32 v66, v66
	v_exp_f32_e32 v67, v67
	v_fmaak_f32 v75, v147, v75, 0x3e2aaaab
	v_fma_f32 v75, v147, v75, 0.5
	v_fma_f32 v75, v147, v75, 1.0
	v_cmp_lt_f32_e64 s[8:9], s84, v147
	v_mul_f32_e64 v75, v75, -v147
	v_fma_f32 v146, -v71, v71, 1.0
	v_add_f32_e32 v64, 1.0, v64
	v_add_f32_e32 v65, 1.0, v65
	v_add_f32_e32 v66, 1.0, v66
	v_add_f32_e32 v67, 1.0, v67
	v_cndmask_b32_e64 v75, v146, v75, s[8:9]
	v_rcp_f32_e32 v64, v64
	v_rcp_f32_e32 v65, v65
	v_sqrt_f32_e32 v73, v73
	v_rcp_f32_e32 v66, v66
	v_rcp_f32_e32 v67, v67
	v_sqrt_f32_e32 v75, v75
	v_pk_mul_f32 v[64:65], v[64:65], v[72:73]
	v_pk_mul_f32 v[66:67], v[66:67], v[74:75]
	v_pk_mul_f32 v[72:73], v[64:65], v[174:175]
	v_pk_mul_f32 v[74:75], v[66:67], v[172:173]
	v_add3_u32 v66, s60, v167, v144
	v_lshl_add_u64 v[64:65], v[142:143], 0, s[22:23]
	ds_write_b128 v66, v[68:71] offset:8192
	ds_write_b128 v66, v[72:75] offset:24576
	v_lshlrev_b64 v[64:65], 2, v[64:65]
	v_lshl_add_u64 v[68:69], s[2:3], 0, v[64:65]
	s_mov_b64 s[2:3], s[48:49]
	v_bitop3_b32 v67, v165, v163, 2 bitop3:0x36
	v_lshl_add_u64 v[72:73], s[2:3], 0, v[64:65]
	s_mov_b64 s[2:3], s[74:75]
	s_add_u32 s2, s2, s30
	s_addc_u32 s3, s3, 0
	v_lshl_add_u64 v[142:143], s[2:3], 0, v[144:145]
	v_add_co_u32_e64 v142, s[8:9], s37, v142
	v_lshlrev_b32_e32 v67, 4, v67
	s_nop 0
	v_addc_co_u32_e64 v143, s[8:9], 0, v143, s[8:9]
	v_add3_u32 v67, v166, v67, v164
	ds_read_b64 v[142:143], v67
	s_mov_b64 s[2:3], s[44:45]
	s_waitcnt lgkmcnt(0)
	v_lshlrev_b32_e32 v168, 16, v142
	v_and_b32_e32 v169, 0xffff0000, v142
	v_lshlrev_b32_e32 v142, 16, v143
	v_and_b32_e32 v143, 0xffff0000, v143
	s_waitcnt vmcnt(6)
	v_add_f32_e32 v60, v60, v216
	v_mul_f32_e32 v60, 0xbfb8aa3b, v60
	v_exp_f32_e32 v60, v60
	v_add_f32_e32 v62, v62, v218
	v_add_f32_e32 v56, v56, v220
	v_mul_f32_e32 v56, 0xbfb8aa3b, v56
	v_exp_f32_e32 v56, v56
	v_add_f32_e32 v58, v58, v222
	v_mul_f32_e32 v58, 0xbfb8aa3b, v58
	v_exp_f32_e32 v58, v58
	v_add_f32_e32 v56, 1.0, v56
	v_rcp_f32_e32 v68, v56
	v_add_f32_e32 v56, v61, v217
	v_mul_f32_e32 v56, 0xbfb8aa3b, v56
	v_exp_f32_e32 v56, v56
	v_add_f32_e32 v60, 1.0, v60
	v_rcp_f32_e32 v60, v60
	v_add_f32_e32 v58, 1.0, v58
	v_add_f32_e32 v56, 1.0, v56
	v_rcp_f32_e32 v61, v56
	v_add_f32_e32 v56, v57, v221
	v_mul_f32_e32 v56, 0xbfb8aa3b, v56
	v_exp_f32_e32 v56, v56
	v_rcp_f32_e32 v70, v58
	v_add_f32_e32 v58, v63, v219
	v_mul_f32_e32 v58, 0xbfb8aa3b, v58
	v_add_f32_e32 v56, 1.0, v56
	v_rcp_f32_e32 v69, v56
	v_pk_mul_f32 v[56:57], v[60:61], s[38:39] op_sel_hi:[1,0]
	v_exp_f32_e32 v58, v58
	v_pk_mul_f32 v[60:61], v[224:225], v[56:57]
	v_mul_f32_e32 v62, 0xbfb8aa3b, v62
	v_pk_add_f32 v[72:73], v[60:61], v[60:61]
	v_mul_f32_e32 v56, 0x3fb8aa3b, v60
	v_fmamk_f32 v57, v72, 0x3ab60b61, v195
	v_exp_f32_e32 v56, v56
	v_fmaak_f32 v57, v72, v57, 0x3d2aaaab
	v_exp_f32_e32 v62, v62
	v_fmaak_f32 v57, v72, v57, 0x3e2aaaab
	v_add_f32_e32 v58, 1.0, v58
	v_fma_f32 v57, v72, v57, 0.5
	v_rcp_f32_e32 v63, v58
	v_add_f32_e32 v58, v59, v223
	v_fma_f32 v57, v72, v57, 1.0
	v_mul_f32_e32 v58, 0xbfb8aa3b, v58
	v_mul_f32_e64 v57, v57, -v72
	v_fma_f32 v60, -v56, v56, 1.0
	v_cmp_lt_f32_e64 s[12:13], s84, v72
	v_add_f32_e32 v62, 1.0, v62
	v_exp_f32_e32 v58, v58
	v_cndmask_b32_e64 v57, v60, v57, s[12:13]
	v_rcp_f32_e32 v62, v62
	v_sqrt_f32_e32 v60, v57
	v_mul_f32_e32 v57, 0x3fb8aa3b, v61
	v_fmamk_f32 v61, v73, 0x3ab60b61, v195
	v_fmaak_f32 v61, v73, v61, 0x3d2aaaab
	v_fmaak_f32 v61, v73, v61, 0x3e2aaaab
	v_add_f32_e32 v58, 1.0, v58
	v_fma_f32 v61, v73, v61, 0.5
	v_rcp_f32_e32 v71, v58
	v_pk_mul_f32 v[58:59], v[62:63], s[38:39] op_sel_hi:[1,0]
	v_fma_f32 v61, v73, v61, 1.0
	v_pk_mul_f32 v[62:63], v[226:227], v[58:59]
	v_cmp_lt_f32_e64 s[8:9], s84, v73
	v_mul_f32_e64 v61, v61, -v73
	v_pk_add_f32 v[72:73], v[62:63], v[62:63]
	v_mul_f32_e32 v58, 0x3fb8aa3b, v62
	v_fmamk_f32 v59, v72, 0x3ab60b61, v195
	v_exp_f32_e32 v58, v58
	v_fmaak_f32 v59, v72, v59, 0x3d2aaaab
	v_fmaak_f32 v59, v72, v59, 0x3e2aaaab
	v_fma_f32 v59, v72, v59, 0.5
	v_fma_f32 v59, v72, v59, 1.0
	v_mul_f32_e64 v59, v59, -v72
	v_fma_f32 v62, -v58, v58, 1.0
	v_cmp_lt_f32_e64 s[12:13], s84, v72
	v_exp_f32_e32 v57, v57
	s_nop 0
	v_cndmask_b32_e64 v59, v62, v59, s[12:13]
	v_sqrt_f32_e32 v62, v59
	v_mul_f32_e32 v59, 0x3fb8aa3b, v63
	v_fmamk_f32 v63, v73, 0x3ab60b61, v195
	v_exp_f32_e32 v59, v59
	v_fmaak_f32 v63, v73, v63, 0x3d2aaaab
	v_fmaak_f32 v63, v73, v63, 0x3e2aaaab
	v_fma_f32 v63, v73, v63, 0.5
	v_fma_f32 v67, -v57, v57, 1.0
	v_fma_f32 v63, v73, v63, 1.0
	v_cndmask_b32_e64 v61, v67, v61, s[8:9]
	v_cmp_lt_f32_e64 s[8:9], s84, v73
	v_mul_f32_e64 v63, v63, -v73
	v_fma_f32 v67, -v59, v59, 1.0
	v_cndmask_b32_e64 v63, v67, v63, s[8:9]
	v_sqrt_f32_e32 v61, v61
	v_sqrt_f32_e32 v63, v63
	v_bitop3_b32 v67, v165, v163, 4 bitop3:0x36
	v_lshlrev_b32_e32 v67, 4, v67
	v_pk_mul_f32 v[60:61], v[68:69], v[60:61]
	v_pk_mul_f32 v[62:63], v[70:71], v[62:63]
	v_pk_mul_f32 v[60:61], v[60:61], v[168:169]
	v_pk_mul_f32 v[62:63], v[62:63], v[142:143]
	ds_write_b128 v66, v[56:59] offset:8256
	ds_write_b128 v66, v[60:63] offset:24640
	v_add3_u32 v67, v166, v67, v164
	v_lshl_add_u64 v[56:57], s[2:3], 0, v[64:65]
	s_mov_b64 s[2:3], s[48:49]
	s_waitcnt lgkmcnt(0)
	s_waitcnt vmcnt(3)
	v_add_f32_e32 v52, v52, v228
	v_lshl_add_u64 v[60:61], s[2:3], 0, v[64:65]
	s_mov_b64 s[2:3], s[74:75]
	s_add_u32 s2, s2, s30
	s_addc_u32 s3, s3, 0
	v_lshl_add_u64 v[68:69], s[2:3], 0, v[144:145]
	v_add_co_u32_e64 v68, s[8:9], s37, v68
	v_mul_f32_e32 v52, 0xbfb8aa3b, v52
	s_nop 0
	v_addc_co_u32_e64 v69, s[8:9], 0, v69, s[8:9]
	v_exp_f32_e32 v52, v52
	v_add_f32_e32 v54, v54, v230
	v_mul_f32_e32 v54, 0xbfb8aa3b, v54
	v_exp_f32_e32 v54, v54
	v_add_f32_e32 v52, 1.0, v52
	v_rcp_f32_e32 v52, v52
	ds_read_b64 v[72:73], v67
	v_add_f32_e32 v54, 1.0, v54
	v_rcp_f32_e32 v54, v54
	s_mov_b64 s[2:3], s[44:45]
	s_waitcnt lgkmcnt(0)
	v_lshlrev_b32_e32 v74, 16, v72
	v_and_b32_e32 v75, 0xffff0000, v72
	v_lshlrev_b32_e32 v72, 16, v73
	v_and_b32_e32 v73, 0xffff0000, v73
	v_add_f32_e32 v48, v48, v232
	v_mul_f32_e32 v48, 0xbfb8aa3b, v48
	v_exp_f32_e32 v48, v48
	v_add_f32_e32 v50, v50, v234
	v_mul_f32_e32 v50, 0xbfb8aa3b, v50
	v_exp_f32_e32 v50, v50
	v_add_f32_e32 v48, 1.0, v48
	v_rcp_f32_e32 v56, v48
	v_add_f32_e32 v48, v53, v229
	v_mul_f32_e32 v48, 0xbfb8aa3b, v48
	v_exp_f32_e32 v48, v48
	v_add_f32_e32 v50, 1.0, v50
	v_rcp_f32_e32 v58, v50
	v_add_f32_e32 v50, v55, v231
	v_add_f32_e32 v48, 1.0, v48
	v_rcp_f32_e32 v53, v48
	v_add_f32_e32 v48, v49, v233
	v_mul_f32_e32 v48, 0xbfb8aa3b, v48
	v_exp_f32_e32 v48, v48
	v_mul_f32_e32 v50, 0xbfb8aa3b, v50
	v_exp_f32_e32 v50, v50
	v_add_f32_e32 v48, 1.0, v48
	v_rcp_f32_e32 v57, v48
	v_pk_mul_f32 v[48:49], v[52:53], s[38:39] op_sel_hi:[1,0]
	v_add_f32_e32 v50, 1.0, v50
	v_pk_mul_f32 v[52:53], v[236:237], v[48:49]
	v_rcp_f32_e32 v55, v50
	v_pk_add_f32 v[60:61], v[52:53], v[52:53]
	v_mul_f32_e32 v48, 0x3fb8aa3b, v52
	v_fmamk_f32 v49, v60, 0x3ab60b61, v195
	v_exp_f32_e32 v48, v48
	v_fmaak_f32 v49, v60, v49, 0x3d2aaaab
	v_fmaak_f32 v49, v60, v49, 0x3e2aaaab
	v_fma_f32 v49, v60, v49, 0.5
	v_fma_f32 v49, v60, v49, 1.0
	v_add_f32_e32 v50, v51, v235
	v_mul_f32_e64 v49, v49, -v60
	v_fma_f32 v52, -v48, v48, 1.0
	v_cmp_lt_f32_e64 s[12:13], s84, v60
	v_mul_f32_e32 v50, 0xbfb8aa3b, v50
	v_exp_f32_e32 v50, v50
	v_cndmask_b32_e64 v49, v52, v49, s[12:13]
	v_sqrt_f32_e32 v52, v49
	v_mul_f32_e32 v49, 0x3fb8aa3b, v53
	v_fmamk_f32 v53, v61, 0x3ab60b61, v195
	v_exp_f32_e32 v49, v49
	v_fmaak_f32 v53, v61, v53, 0x3d2aaaab
	v_fmaak_f32 v53, v61, v53, 0x3e2aaaab
	v_fma_f32 v53, v61, v53, 0.5
	v_add_f32_e32 v50, 1.0, v50
	v_fma_f32 v53, v61, v53, 1.0
	v_rcp_f32_e32 v59, v50
	v_pk_mul_f32 v[50:51], v[54:55], s[38:39] op_sel_hi:[1,0]
	v_cmp_lt_f32_e64 s[8:9], s84, v61
	v_mul_f32_e64 v53, v53, -v61
	v_fma_f32 v60, -v49, v49, 1.0
	v_pk_mul_f32 v[54:55], v[238:239], v[50:51]
	v_cndmask_b32_e64 v53, v60, v53, s[8:9]
	v_pk_add_f32 v[60:61], v[54:55], v[54:55]
	v_mul_f32_e32 v50, 0x3fb8aa3b, v54
	v_fmamk_f32 v51, v60, 0x3ab60b61, v195
	v_exp_f32_e32 v50, v50
	v_fmaak_f32 v51, v60, v51, 0x3d2aaaab
	v_fmaak_f32 v51, v60, v51, 0x3e2aaaab
	v_fma_f32 v51, v60, v51, 0.5
	v_fma_f32 v51, v60, v51, 1.0
	v_mul_f32_e64 v51, v51, -v60
	v_fma_f32 v54, -v50, v50, 1.0
	v_cmp_lt_f32_e64 s[12:13], s84, v60
	v_cmp_lt_f32_e64 s[8:9], s84, v61
	v_sqrt_f32_e32 v53, v53
	v_cndmask_b32_e64 v51, v54, v51, s[12:13]
	v_sqrt_f32_e32 v54, v51
	v_mul_f32_e32 v51, 0x3fb8aa3b, v55
	v_fmamk_f32 v55, v61, 0x3ab60b61, v195
	v_exp_f32_e32 v51, v51
	v_fmaak_f32 v55, v61, v55, 0x3d2aaaab
	v_fmaak_f32 v55, v61, v55, 0x3e2aaaab
	v_fma_f32 v55, v61, v55, 0.5
	v_fma_f32 v55, v61, v55, 1.0
	v_mul_f32_e64 v55, v55, -v61
	v_fma_f32 v60, -v51, v51, 1.0
	v_cndmask_b32_e64 v55, v60, v55, s[8:9]
	v_sqrt_f32_e32 v55, v55
	v_pk_mul_f32 v[52:53], v[56:57], v[52:53]
	v_bitop3_b32 v60, v165, v163, 6 bitop3:0x36
	v_pk_mul_f32 v[52:53], v[52:53], v[74:75]
	v_pk_mul_f32 v[54:55], v[58:59], v[54:55]
	v_lshlrev_b32_e32 v60, 4, v60
	v_pk_mul_f32 v[54:55], v[54:55], v[72:73]
	ds_write_b128 v66, v[48:51] offset:8320
	ds_write_b128 v66, v[52:55] offset:24704
	v_add3_u32 v60, v166, v60, v164
	v_lshl_add_u64 v[48:49], s[2:3], 0, v[64:65]
	s_mov_b64 s[2:3], s[48:49]
	s_waitcnt lgkmcnt(0)
	s_waitcnt vmcnt(0)
	v_add_f32_e32 v12, v12, v240
	v_lshl_add_u64 v[52:53], s[2:3], 0, v[64:65]
	s_mov_b64 s[2:3], s[74:75]
	s_add_u32 s2, s2, s30
	s_addc_u32 s3, s3, 0
	v_lshl_add_u64 v[56:57], s[2:3], 0, v[144:145]
	v_add_co_u32_e64 v56, s[8:9], s37, v56
	v_mul_f32_e32 v12, 0xbfb8aa3b, v12
	s_nop 0
	v_addc_co_u32_e64 v57, s[8:9], 0, v57, s[8:9]
	v_exp_f32_e32 v12, v12
	v_add_f32_e32 v14, v14, v242
	v_mul_f32_e32 v14, 0xbfb8aa3b, v14
	v_exp_f32_e32 v14, v14
	v_add_f32_e32 v12, 1.0, v12
	v_rcp_f32_e32 v12, v12
	ds_read_b64 v[60:61], v60
	v_add_f32_e32 v14, 1.0, v14
	v_rcp_f32_e32 v14, v14
	s_waitcnt lgkmcnt(0)
	v_lshlrev_b32_e32 v62, 16, v60
	v_and_b32_e32 v63, 0xffff0000, v60
	v_lshlrev_b32_e32 v60, 16, v61
	v_and_b32_e32 v61, 0xffff0000, v61
	v_add_f32_e32 v8, v8, v244
	v_mul_f32_e32 v8, 0xbfb8aa3b, v8
	v_exp_f32_e32 v8, v8
	v_add_f32_e32 v10, v10, v246
	v_mul_f32_e32 v10, 0xbfb8aa3b, v10
	v_exp_f32_e32 v10, v10
	v_add_f32_e32 v8, 1.0, v8
	v_rcp_f32_e32 v48, v8
	v_add_f32_e32 v8, v13, v241
	v_mul_f32_e32 v8, 0xbfb8aa3b, v8
	v_exp_f32_e32 v8, v8
	v_add_f32_e32 v10, 1.0, v10
	v_rcp_f32_e32 v50, v10
	v_add_f32_e32 v10, v15, v243
	v_add_f32_e32 v8, 1.0, v8
	v_rcp_f32_e32 v13, v8
	v_add_f32_e32 v8, v9, v245
	v_mul_f32_e32 v8, 0xbfb8aa3b, v8
	v_exp_f32_e32 v8, v8
	v_mul_f32_e32 v10, 0xbfb8aa3b, v10
	v_exp_f32_e32 v10, v10
	v_add_f32_e32 v8, 1.0, v8
	v_rcp_f32_e32 v49, v8
	v_pk_mul_f32 v[8:9], v[12:13], s[38:39] op_sel_hi:[1,0]
	v_add_f32_e32 v10, 1.0, v10
	v_pk_mul_f32 v[12:13], v[248:249], v[8:9]
	v_rcp_f32_e32 v15, v10
	v_pk_add_f32 v[52:53], v[12:13], v[12:13]
	v_mul_f32_e32 v8, 0x3fb8aa3b, v12
	v_fmamk_f32 v9, v52, 0x3ab60b61, v195
	v_exp_f32_e32 v8, v8
	v_fmaak_f32 v9, v52, v9, 0x3d2aaaab
	v_fmaak_f32 v9, v52, v9, 0x3e2aaaab
	v_fma_f32 v9, v52, v9, 0.5
	v_fma_f32 v9, v52, v9, 1.0
	v_add_f32_e32 v10, v11, v247
	v_mul_f32_e64 v9, v9, -v52
	v_fma_f32 v12, -v8, v8, 1.0
	v_cmp_lt_f32_e64 s[12:13], s84, v52
	v_mul_f32_e32 v10, 0xbfb8aa3b, v10
	v_exp_f32_e32 v10, v10
	v_cndmask_b32_e64 v9, v12, v9, s[12:13]
	v_sqrt_f32_e32 v12, v9
	v_mul_f32_e32 v9, 0x3fb8aa3b, v13
	v_fmamk_f32 v13, v53, 0x3ab60b61, v195
	v_exp_f32_e32 v9, v9
	v_fmaak_f32 v13, v53, v13, 0x3d2aaaab
	v_fmaak_f32 v13, v53, v13, 0x3e2aaaab
	v_fma_f32 v13, v53, v13, 0.5
	v_add_f32_e32 v10, 1.0, v10
	v_fma_f32 v13, v53, v13, 1.0
	v_rcp_f32_e32 v51, v10
	v_pk_mul_f32 v[10:11], v[14:15], s[38:39] op_sel_hi:[1,0]
	v_cmp_lt_f32_e64 s[8:9], s84, v53
	v_mul_f32_e64 v13, v13, -v53
	v_fma_f32 v52, -v9, v9, 1.0
	v_pk_mul_f32 v[14:15], v[250:251], v[10:11]
	v_cndmask_b32_e64 v13, v52, v13, s[8:9]
	v_pk_add_f32 v[52:53], v[14:15], v[14:15]
	v_mul_f32_e32 v10, 0x3fb8aa3b, v14
	v_fmamk_f32 v11, v52, 0x3ab60b61, v195
	v_exp_f32_e32 v10, v10
	v_fmaak_f32 v11, v52, v11, 0x3d2aaaab
	v_fmaak_f32 v11, v52, v11, 0x3e2aaaab
	v_fma_f32 v11, v52, v11, 0.5
	v_fma_f32 v11, v52, v11, 1.0
	v_mul_f32_e64 v11, v11, -v52
	v_fma_f32 v14, -v10, v10, 1.0
	v_cmp_lt_f32_e64 s[12:13], s84, v52
	v_cmp_lt_f32_e64 s[8:9], s84, v53
	v_sqrt_f32_e32 v13, v13
	v_cndmask_b32_e64 v11, v14, v11, s[12:13]
	v_sqrt_f32_e32 v14, v11
	v_mul_f32_e32 v11, 0x3fb8aa3b, v15
	v_fmamk_f32 v15, v53, 0x3ab60b61, v195
	v_exp_f32_e32 v11, v11
	v_fmaak_f32 v15, v53, v15, 0x3d2aaaab
	v_fmaak_f32 v15, v53, v15, 0x3e2aaaab
	v_fma_f32 v15, v53, v15, 0.5
	v_fma_f32 v15, v53, v15, 1.0
	v_mul_f32_e64 v15, v15, -v53
	v_fma_f32 v52, -v11, v11, 1.0
	v_cndmask_b32_e64 v15, v52, v15, s[8:9]
	v_sqrt_f32_e32 v15, v15
	v_pk_mul_f32 v[12:13], v[48:49], v[12:13]
	v_cmp_lt_i32_e64 s[8:9], 0, v141
	v_pk_mul_f32 v[12:13], v[12:13], v[62:63]
	v_pk_mul_f32 v[14:15], v[50:51], v[14:15]
	s_nop 0
	v_pk_mul_f32 v[14:15], v[14:15], v[60:61]
	ds_write_b128 v66, v[8:11] offset:8384
	ds_write_b128 v66, v[12:15] offset:24768
	v_and_b32_e32 v9, 63, v162
	v_lshlrev_b32_e32 v64, 2, v9
	v_lshl_or_b32 v8, v141, 12, v64
	v_add_u32_e32 v8, s60, v8
	s_waitcnt lgkmcnt(0)
	s_barrier
	ds_read2st64_b32 v[10:11], v8 offset0:32 offset1:33
	ds_read2st64_b32 v[12:13], v8 offset0:96 offset1:97
	ds_read2st64_b32 v[14:15], v8 offset0:34 offset1:35
	ds_read2st64_b32 v[48:49], v8 offset0:98 offset1:99
	v_lshl_add_u32 v9, v9, 3, s60
	s_waitcnt lgkmcnt(2)
	v_fma_f32 v12, 0, v10, v12
	v_fmac_f32_e32 v13, v12, v11
	v_mul_f32_e32 v10, v10, v11
	s_waitcnt lgkmcnt(0)
	v_fma_f32 v11, v13, v14, v48
	ds_read2st64_b32 v[12:13], v8 offset0:36 offset1:37
	ds_read2st64_b32 v[50:51], v8 offset0:100 offset1:101
	v_fmac_f32_e32 v49, v11, v15
	v_mov_b32_e32 v58, v14
	v_mul_f32_e32 v14, v10, v14
	v_mul_f32_e32 v14, v14, v15
	s_waitcnt lgkmcnt(0)
	v_fma_f32 v11, v49, v12, v50
	ds_read2st64_b32 v[48:49], v8 offset0:38 offset1:39
	ds_read2st64_b32 v[52:53], v8 offset0:102 offset1:103
	v_fmac_f32_e32 v51, v11, v13
	s_waitcnt lgkmcnt(1)
	v_mov_b32_e32 v62, v48
	s_waitcnt lgkmcnt(0)
	v_fma_f32 v11, v51, v48, v52
	ds_read2st64_b32 v[50:51], v8 offset0:40 offset1:41
	ds_read2st64_b32 v[54:55], v8 offset0:104 offset1:105
	v_fmac_f32_e32 v53, v11, v49
	s_waitcnt lgkmcnt(1)
	v_mov_b32_e32 v59, v51
	s_waitcnt lgkmcnt(0)
	v_fmac_f32_e32 v54, v53, v50
	ds_read2st64_b32 v[52:53], v8 offset0:42 offset1:43
	ds_read2st64_b32 v[56:57], v8 offset0:106 offset1:107
	v_mov_b32_e32 v11, v54
	v_mov_b32_e32 v54, v15
	v_pk_fma_f32 v[10:11], v[10:11], v[58:59], v[54:55]
	v_mov_b32_e32 v58, v13
	v_mov_b32_e32 v15, v11
	v_mov_b32_e32 v10, v12
	s_waitcnt lgkmcnt(1)
	v_mov_b32_e32 v11, v52
	v_pk_mul_f32 v[54:55], v[14:15], v[10:11]
	v_mov_b32_e32 v12, v13
	s_waitcnt lgkmcnt(0)
	v_mov_b32_e32 v59, v56
	v_pk_mul_f32 v[12:13], v[54:55], v[12:13]
	v_pk_fma_f32 v[10:11], v[14:15], v[10:11], v[58:59]
	v_and_b32_e32 v56, 0x1fffffc0, v161
	v_mov_b32_e32 v10, v12
	ds_read2st64_b32 v[14:15], v8 offset0:44 offset1:45
	ds_read2st64_b32 v[54:55], v8 offset0:108 offset1:109
	ds_read2st64_b32 v[58:59], v8 offset0:46 offset1:47
	ds_read2st64_b32 v[60:61], v8 offset0:110 offset1:111
	v_lshl_add_u32 v65, v56, 3, v9
	v_mov_b32_e32 v63, v53
	v_pk_mul_f32 v[12:13], v[12:13], v[48:49]
	v_mov_b32_e32 v48, v49
	v_mov_b32_e32 v56, v49
	v_pk_mul_f32 v[12:13], v[12:13], v[48:49]
	v_pk_fma_f32 v[10:11], v[10:11], v[62:63], v[56:57]
	v_mov_b32_e32 v56, v51
	v_mov_b32_e32 v13, v11
	v_mov_b32_e32 v10, v50
	s_waitcnt lgkmcnt(3)
	v_mov_b32_e32 v11, v14
	v_pk_mul_f32 v[48:49], v[12:13], v[10:11]
	v_mov_b32_e32 v50, v51
	s_waitcnt lgkmcnt(2)
	v_mov_b32_e32 v57, v54
	v_pk_mul_f32 v[48:49], v[48:49], v[50:51]
	v_pk_fma_f32 v[10:11], v[12:13], v[10:11], v[56:57]
	v_mov_b32_e32 v12, v52
	v_mov_b32_e32 v10, v48
	v_mov_b32_e32 v13, v15
	v_pk_mul_f32 v[48:49], v[48:49], v[52:53]
	v_mov_b32_e32 v50, v53
	v_mov_b32_e32 v54, v53
	v_pk_mul_f32 v[48:49], v[48:49], v[50:51]
	v_pk_fma_f32 v[10:11], v[10:11], v[12:13], v[54:55]
	v_mov_b32_e32 v50, v15
	v_mov_b32_e32 v49, v11
	v_mov_b32_e32 v10, v14
	s_waitcnt lgkmcnt(1)
	v_mov_b32_e32 v11, v58
	v_pk_mul_f32 v[12:13], v[48:49], v[10:11]
	v_mov_b32_e32 v14, v15
	s_waitcnt lgkmcnt(0)
	v_mov_b32_e32 v51, v60
	v_pk_mul_f32 v[12:13], v[12:13], v[14:15]
	v_pk_fma_f32 v[10:11], v[48:49], v[10:11], v[50:51]
	v_mov_b32_e32 v14, v59
	v_mov_b32_e32 v10, v12
	v_pk_mul_f32 v[12:13], v[12:13], v[58:59]
	v_mov_b32_e32 v60, v59
	v_pk_mul_f32 v[12:13], v[12:13], v[14:15]
	v_pk_fma_f32 v[10:11], v[10:11], v[58:59], v[60:61]
	s_nop 0
	v_mov_b32_e32 v13, v11
	v_sub_u32_e32 v10, v9, v64
	ds_write_b64 v65, v[12:13] offset:40960
	s_waitcnt lgkmcnt(0)
	s_barrier
	ds_read_b32 v10, v10 offset:43008
	s_and_saveexec_b64 s[2:3], s[8:9]
	s_cbranch_execz .LBB0_359
	ds_read_b64 v[12:13], v9 offset:40960
	s_waitcnt lgkmcnt(0)
	v_fmac_f32_e32 v13, v10, v12
	v_mov_b32_e32 v10, v13
	s_or_b64 exec, exec, s[2:3]
	v_cmp_lt_i32_e64 s[8:9], 1, v141
	s_and_saveexec_b64 s[2:3], s[8:9]
	s_cbranch_execnz .LBB0_360

.LBB0_363:
	s_or_b64 exec, exec, s[2:3]
	s_mov_b64 s[2:3], s[74:75]
	ds_read2st64_b32 v[12:13], v8 offset0:32 offset1:33
	ds_read2st64_b32 v[14:15], v8 offset0:96 offset1:97
	v_mov_b32_e32 v162, v191
	v_mov_b32_e32 v163, v191
	s_mov_b64 s[2:3], s[74:75]
	v_mov_b32_e32 v143, v145
	s_waitcnt lgkmcnt(0)
	v_fma_f32 v9, v10, v12, v14
	v_fmac_f32_e32 v15, v9, v13
	ds_write2st64_b32 v8, v9, v15 offset0:176 offset1:177
	ds_read2st64_b32 v[10:11], v8 offset0:34 offset1:35
	ds_read2st64_b32 v[12:13], v8 offset0:98 offset1:99
	v_readlane_b32 s40, v254, 22
	v_readlane_b32 s44, v254, 26
	v_readlane_b32 s45, v254, 27
	v_readlane_b32 s48, v254, 30
	s_waitcnt lgkmcnt(0)
	v_fma_f32 v9, v15, v10, v12
	v_fmac_f32_e32 v13, v9, v11
	ds_write2st64_b32 v8, v9, v13 offset0:178 offset1:179
	ds_read2st64_b32 v[10:11], v8 offset0:36 offset1:37
	ds_read2st64_b32 v[14:15], v8 offset0:100 offset1:101
	v_readlane_b32 s49, v254, 31
	s_mov_b64 s[8:9], s[48:49]
	v_readlane_b32 s41, v254, 23
	v_readlane_b32 s42, v254, 24
	s_waitcnt lgkmcnt(0)
	v_fma_f32 v9, v13, v10, v14
	v_fmac_f32_e32 v15, v9, v11
	ds_write2st64_b32 v8, v9, v15 offset0:180 offset1:181
	ds_read2st64_b32 v[10:11], v8 offset0:38 offset1:39
	ds_read2st64_b32 v[12:13], v8 offset0:102 offset1:103
	v_readlane_b32 s43, v254, 25
	v_readlane_b32 s46, v254, 28
	v_readlane_b32 s47, v254, 29
	v_readlane_b32 s50, v254, 32
	s_waitcnt lgkmcnt(0)
	v_fma_f32 v9, v15, v10, v12
	v_fmac_f32_e32 v13, v9, v11
	ds_write2st64_b32 v8, v9, v13 offset0:182 offset1:183
	ds_read2st64_b32 v[10:11], v8 offset0:40 offset1:41
	ds_read2st64_b32 v[14:15], v8 offset0:104 offset1:105
	v_readlane_b32 s51, v254, 33
	v_readlane_b32 s52, v254, 34
	v_readlane_b32 s53, v254, 35
	v_readlane_b32 s54, v254, 36
	s_waitcnt lgkmcnt(0)
	v_fma_f32 v9, v13, v10, v14
	v_fmac_f32_e32 v15, v9, v11
	ds_write2st64_b32 v8, v9, v15 offset0:184 offset1:185
	ds_read2st64_b32 v[10:11], v8 offset0:42 offset1:43
	ds_read2st64_b32 v[12:13], v8 offset0:106 offset1:107
	v_readlane_b32 s55, v254, 37
	s_waitcnt lgkmcnt(0)
	v_fma_f32 v9, v15, v10, v12
	v_fmac_f32_e32 v13, v9, v11
	ds_write2st64_b32 v8, v9, v13 offset0:186 offset1:187
	ds_read2st64_b32 v[10:11], v8 offset0:44 offset1:45
	ds_read2st64_b32 v[14:15], v8 offset0:108 offset1:109
	s_waitcnt lgkmcnt(0)
	v_fma_f32 v9, v13, v10, v14
	v_fmac_f32_e32 v15, v9, v11
	ds_write2st64_b32 v8, v9, v15 offset0:188 offset1:189
	ds_read2st64_b32 v[10:11], v8 offset0:46 offset1:47
	ds_read2st64_b32 v[12:13], v8 offset0:110 offset1:111
	s_waitcnt lgkmcnt(0)
	v_fma_f32 v9, v15, v10, v12
	v_fmac_f32_e32 v13, v9, v11
	ds_write2st64_b32 v8, v9, v13 offset0:190 offset1:191
	s_waitcnt lgkmcnt(0)
	s_barrier
	s_add_u32 s2, s2, s31
	v_and_b32_e32 v165, 15, v162
	v_lshrrev_b32_e32 v170, 4, v162
	v_bfe_u32 v171, v162, 4, 2
	v_bfe_u32 v164, v162, 1, 3
	v_ashrrev_i32_e32 v161, 6, v162
	v_lshlrev_b32_e32 v142, 7, v165
	v_bitop3_b32 v8, v170, v164, 3 bitop3:0x6c
	v_bitop3_b32 v13, v171, v164, 4 bitop3:0x36
	v_lshl_or_b32 v12, v161, 11, v142
	v_lshlrev_b32_e32 v8, 4, v8
	v_lshlrev_b32_e32 v13, 4, v13
	v_add3_u32 v8, s60, v8, v12
	v_add3_u32 v12, s60, v13, v12
	s_addc_u32 s3, s3, 0
	v_lshlrev_b32_e32 v144, 4, v171
	ds_read_b128 v[8:11], v8
	ds_read_b128 v[72:75], v12
	v_lshl_add_u64 v[12:13], s[2:3], 0, v[144:145]
	s_mov_b64 s[2:3], 0x3980000
	v_lshl_add_u64 v[166:167], v[12:13], 0, s[2:3]
	s_mov_b64 s[2:3], 0x39a0000
	v_lshl_add_u64 v[168:169], v[12:13], 0, s[2:3]
	v_mul_u32_u24_e32 v184, 0xf0, v171
	v_lshl_add_u32 v184, v165, 4, v184
	v_mov_b32_e32 v185, v145
	v_lshl_add_u64 v[60:61], v[166:167], 0, v[184:185]
	v_lshl_add_u64 v[62:63], v[168:169], 0, v[184:185]
	s_mov_b64 s[98:99], 0x1000
	v_lshl_add_u64 v[174:175], v[60:61], 0, s[98:99]
	v_lshl_add_u64 v[176:177], v[62:63], 0, s[98:99]
	v_lshrrev_b32_e32 v172, 1, v162
	v_lshlrev_b32_e32 v141, 4, v161
	s_mov_b64 s[2:3], s[44:45]
	v_lshlrev_b32_e32 v142, 2, v171
	v_mov_b32_e32 v143, v145
	global_load_dwordx4 v[68:71], v[60:61], off
	global_load_dwordx4 v[64:67], v[62:63], off
	global_load_dwordx4 v[216:219], v[60:61], off offset:1024
	global_load_dwordx4 v[220:223], v[62:63], off offset:1024
	global_load_dwordx4 v[56:59], v[62:63], off offset:2048
	global_load_dwordx4 v[224:227], v[60:61], off offset:3072
	global_load_dwordx4 v[228:231], v[62:63], off offset:3072
	global_load_dwordx4 v[60:63], v[60:61], off offset:2048
	global_load_dwordx4 v[52:55], v[174:175], off
	global_load_dwordx4 v[48:51], v[176:177], off
	global_load_dwordx4 v[232:235], v[174:175], off offset:1024
	global_load_dwordx4 v[236:239], v[176:177], off offset:1024
	global_load_dwordx4 v[12:15], v[174:175], off offset:2048
	global_load_dwordx4 v[248:251], v[176:177], off offset:2048
	global_load_dwordx4 v[240:243], v[174:175], off offset:3072
	global_load_dwordx4 v[244:247], v[176:177], off offset:3072
	v_or_b32_e32 v146, s22, v142
	v_ashrrev_i32_e32 v147, 31, v146
	v_lshlrev_b64 v[146:147], 2, v[146:147]
	s_add_u32 s98, s74, s30
	s_addc_u32 s99, s75, 0
	s_add_u32 s98, s98, 0x122e6000
	s_addc_u32 s99, s99, 0
	v_lshl_add_u64 v[182:183], s[98:99], 0, v[144:145]
	v_lshl_add_u64 v[174:175], s[44:45], 0, v[146:147]
	v_lshl_add_u64 v[176:177], s[48:49], 0, v[146:147]
	global_load_dwordx4 v[146:149], v[174:175], off offset:2048
	global_load_dwordx4 v[178:181], v[176:177], off offset:2048
	global_load_dwordx4 v[182:185], v[182:183], off offset:2048
	s_waitcnt vmcnt(0) lgkmcnt(0)
	v_mfma_f32_16x16x32_bf16 v[68:71], v[68:71], v[8:11], 0
	v_mfma_f32_16x16x32_bf16 v[64:67], v[64:67], v[8:11], 0
	v_mfma_f32_16x16x32_bf16 v[60:63], v[60:63], v[8:11], 0
	v_mfma_f32_16x16x32_bf16 v[56:59], v[56:59], v[8:11], 0
	v_mfma_f32_16x16x32_bf16 v[52:55], v[52:55], v[8:11], 0
	v_mfma_f32_16x16x32_bf16 v[48:51], v[48:51], v[8:11], 0
	v_mfma_f32_16x16x32_bf16 v[12:15], v[12:15], v[8:11], 0
	v_mfma_f32_16x16x32_bf16 v[8:11], v[248:251], v[8:11], 0
	v_mfma_f32_16x16x32_bf16 v[68:71], v[216:219], v[72:75], v[68:71]
	v_mfma_f32_16x16x32_bf16 v[64:67], v[220:223], v[72:75], v[64:67]
	v_mfma_f32_16x16x32_bf16 v[60:63], v[224:227], v[72:75], v[60:63]
	v_mfma_f32_16x16x32_bf16 v[56:59], v[228:231], v[72:75], v[56:59]
	v_mfma_f32_16x16x32_bf16 v[52:55], v[232:235], v[72:75], v[52:55]
	v_mfma_f32_16x16x32_bf16 v[48:51], v[236:239], v[72:75], v[48:51]
	v_mfma_f32_16x16x32_bf16 v[12:15], v[240:243], v[72:75], v[12:15]
	v_mfma_f32_16x16x32_bf16 v[8:11], v[244:247], v[72:75], v[8:11]
	v_lshl_add_u64 v[248:249], s[98:99], 0, v[144:145]
	global_load_dwordx4 v[216:219], v[174:175], off offset:2112
	global_load_dwordx4 v[220:223], v[176:177], off offset:2112
	global_load_dwordx4 v[224:227], v[248:249], off offset:2112
	global_load_dwordx4 v[228:231], v[174:175], off offset:2176
	global_load_dwordx4 v[232:235], v[176:177], off offset:2176
	global_load_dwordx4 v[236:239], v[248:249], off offset:2176
	global_load_dwordx4 v[240:243], v[174:175], off offset:2240
	global_load_dwordx4 v[244:247], v[176:177], off offset:2240
	global_load_dwordx4 v[248:251], v[248:249], off offset:2240
	v_or_b32_e32 v72, v141, v165
	v_and_b32_e32 v73, 8, v172
	v_lshlrev_b32_e32 v165, 7, v72
	v_add_u32_e32 v167, s60, v73
	v_lshlrev_b32_e32 v176, 8, v72
	v_lshl_add_u64 v[72:73], v[142:143], 0, s[22:23]
	s_mov_b64 s[2:3], s[74:75]
	s_add_u32 s2, s2, s30
	s_addc_u32 s3, s3, 0
	v_lshl_add_u64 v[168:169], s[2:3], 0, v[144:145]
	v_add_co_u32_e64 v168, s[8:9], s37, v168
	v_bfe_u32 v166, v170, 1, 1
	s_nop 0
	v_addc_co_u32_e64 v169, s[8:9], 0, v169, s[8:9]
	v_bitop3_b32 v172, v166, v172, 7 bitop3:0x78
	v_lshlrev_b32_e32 v172, 4, v172
	v_add3_u32 v172, v167, v172, v165
	ds_read_b64 v[172:173], v172
	s_mov_b64 s[2:3], s[44:45]
	s_waitcnt lgkmcnt(0)
	v_lshlrev_b32_e32 v174, 16, v172
	v_and_b32_e32 v175, 0xffff0000, v172
	v_lshlrev_b32_e32 v172, 16, v173
	v_and_b32_e32 v173, 0xffff0000, v173
	v_add_f32_e32 v68, v68, v146
	v_add_f32_e32 v69, v69, v147
	v_mul_f32_e32 v68, 0xbfb8aa3b, v68
	v_mul_f32_e32 v69, 0xbfb8aa3b, v69
	v_exp_f32_e32 v68, v68
	v_exp_f32_e32 v69, v69
	v_add_f32_e32 v64, v64, v178
	v_add_f32_e32 v65, v65, v179
	v_add_f32_e32 v68, 1.0, v68
	v_add_f32_e32 v69, 1.0, v69
	v_rcp_f32_e32 v68, v68
	v_rcp_f32_e32 v69, v69
	v_add_f32_e32 v70, v70, v148
	v_add_f32_e32 v71, v71, v149
	v_mul_f32_e32 v70, 0xbfb8aa3b, v70
	v_pk_mul_f32 v[68:69], v[68:69], s[38:39] op_sel_hi:[1,0]
	v_mul_f32_e32 v71, 0xbfb8aa3b, v71
	v_pk_mul_f32 v[72:73], v[182:183], v[68:69]
	v_exp_f32_e32 v70, v70
	v_pk_add_f32 v[146:147], v[72:73], v[72:73]
	v_mul_f32_e32 v68, 0x3fb8aa3b, v72
	v_fmamk_f32 v69, v146, 0x3ab60b61, v195
	v_exp_f32_e32 v68, v68
	v_fmaak_f32 v69, v146, v69, 0x3d2aaaab
	v_fmaak_f32 v69, v146, v69, 0x3e2aaaab
	v_exp_f32_e32 v71, v71
	v_fma_f32 v69, v146, v69, 0.5
	v_fma_f32 v69, v146, v69, 1.0
	v_mul_f32_e64 v69, v69, -v146
	v_fma_f32 v72, -v68, v68, 1.0
	v_cmp_lt_f32_e64 s[12:13], s84, v146
	v_add_f32_e32 v70, 1.0, v70
	v_add_f32_e32 v71, 1.0, v71
	v_cndmask_b32_e64 v69, v72, v69, s[12:13]
	v_sqrt_f32_e32 v72, v69
	v_mul_f32_e32 v69, 0x3fb8aa3b, v73
	v_fmamk_f32 v73, v147, 0x3ab60b61, v195
	v_rcp_f32_e32 v70, v70
	v_rcp_f32_e32 v71, v71
	v_exp_f32_e32 v69, v69
	v_fmaak_f32 v73, v147, v73, 0x3d2aaaab
	v_fmaak_f32 v73, v147, v73, 0x3e2aaaab
	v_fma_f32 v73, v147, v73, 0.5
	v_fma_f32 v73, v147, v73, 1.0
	v_pk_mul_f32 v[70:71], v[70:71], s[38:39] op_sel_hi:[1,0]
	v_cmp_lt_f32_e64 s[8:9], s84, v147
	v_mul_f32_e64 v73, v73, -v147
	v_fma_f32 v146, -v69, v69, 1.0
	v_pk_mul_f32 v[74:75], v[184:185], v[70:71]
	v_cndmask_b32_e64 v73, v146, v73, s[8:9]
	v_pk_add_f32 v[146:147], v[74:75], v[74:75]
	v_mul_f32_e32 v70, 0x3fb8aa3b, v74
	v_fmamk_f32 v71, v146, 0x3ab60b61, v195
	v_exp_f32_e32 v70, v70
	v_fmaak_f32 v71, v146, v71, 0x3d2aaaab
	v_fmaak_f32 v71, v146, v71, 0x3e2aaaab
	v_fma_f32 v71, v146, v71, 0.5
	v_fma_f32 v71, v146, v71, 1.0
	v_mul_f32_e64 v71, v71, -v146
	v_fma_f32 v74, -v70, v70, 1.0
	v_cmp_lt_f32_e64 s[12:13], s84, v146
	v_add_f32_e32 v66, v66, v180
	v_add_f32_e32 v67, v67, v181
	v_cndmask_b32_e64 v71, v74, v71, s[12:13]
	v_sqrt_f32_e32 v74, v71
	v_mul_f32_e32 v71, 0x3fb8aa3b, v75
	v_fmamk_f32 v75, v147, 0x3ab60b61, v195
	v_mul_f32_e32 v64, 0xbfb8aa3b, v64
	v_mul_f32_e32 v65, 0xbfb8aa3b, v65
	v_mul_f32_e32 v66, 0xbfb8aa3b, v66
	v_mul_f32_e32 v67, 0xbfb8aa3b, v67
	v_exp_f32_e32 v71, v71
	v_fmaak_f32 v75, v147, v75, 0x3d2aaaab
	v_exp_f32_e32 v64, v64
	v_exp_f32_e32 v65, v65
	v_exp_f32_e32 v66, v66
	v_exp_f32_e32 v67, v67
	v_fmaak_f32 v75, v147, v75, 0x3e2aaaab
	v_fma_f32 v75, v147, v75, 0.5
	v_fma_f32 v75, v147, v75, 1.0
	v_cmp_lt_f32_e64 s[8:9], s84, v147
	v_mul_f32_e64 v75, v75, -v147
	v_fma_f32 v146, -v71, v71, 1.0
	v_add_f32_e32 v64, 1.0, v64
	v_add_f32_e32 v65, 1.0, v65
	v_add_f32_e32 v66, 1.0, v66
	v_add_f32_e32 v67, 1.0, v67
	v_cndmask_b32_e64 v75, v146, v75, s[8:9]
	v_rcp_f32_e32 v64, v64
	v_rcp_f32_e32 v65, v65
	v_sqrt_f32_e32 v73, v73
	v_rcp_f32_e32 v66, v66
	v_rcp_f32_e32 v67, v67
	v_sqrt_f32_e32 v75, v75
	v_pk_mul_f32 v[64:65], v[64:65], v[72:73]
	v_pk_mul_f32 v[66:67], v[66:67], v[74:75]
	v_pk_mul_f32 v[72:73], v[64:65], v[174:175]
	v_pk_mul_f32 v[74:75], v[66:67], v[172:173]
	v_add3_u32 v66, s60, v176, v144
	v_lshl_add_u64 v[64:65], v[142:143], 0, s[24:25]
	ds_write_b128 v66, v[68:71] offset:8192
	ds_write_b128 v66, v[72:75] offset:24576
	v_lshlrev_b64 v[64:65], 2, v[64:65]
	v_lshl_add_u64 v[68:69], s[2:3], 0, v[64:65]
	s_mov_b64 s[2:3], s[48:49]
	v_bitop3_b32 v67, v166, v164, 2 bitop3:0x36
	v_lshl_add_u64 v[72:73], s[2:3], 0, v[64:65]
	s_mov_b64 s[2:3], s[74:75]
	s_add_u32 s2, s2, s30
	s_addc_u32 s3, s3, 0
	v_lshl_add_u64 v[142:143], s[2:3], 0, v[144:145]
	v_add_co_u32_e64 v142, s[8:9], s37, v142
	v_lshlrev_b32_e32 v67, 4, v67
	s_nop 0
	v_addc_co_u32_e64 v143, s[8:9], 0, v143, s[8:9]
	v_add3_u32 v67, v167, v67, v165
	ds_read_b64 v[142:143], v67
	s_mov_b64 s[2:3], s[44:45]
	s_waitcnt lgkmcnt(0)
	v_lshlrev_b32_e32 v168, 16, v142
	v_and_b32_e32 v169, 0xffff0000, v142
	v_lshlrev_b32_e32 v142, 16, v143
	v_and_b32_e32 v143, 0xffff0000, v143
	s_waitcnt vmcnt(6)
	v_add_f32_e32 v60, v60, v216
	v_mul_f32_e32 v60, 0xbfb8aa3b, v60
	v_exp_f32_e32 v60, v60
	v_add_f32_e32 v62, v62, v218
	v_add_f32_e32 v56, v56, v220
	v_mul_f32_e32 v56, 0xbfb8aa3b, v56
	v_exp_f32_e32 v56, v56
	v_add_f32_e32 v58, v58, v222
	v_mul_f32_e32 v58, 0xbfb8aa3b, v58
	v_exp_f32_e32 v58, v58
	v_add_f32_e32 v56, 1.0, v56
	v_rcp_f32_e32 v68, v56
	v_add_f32_e32 v56, v61, v217
	v_mul_f32_e32 v56, 0xbfb8aa3b, v56
	v_exp_f32_e32 v56, v56
	v_add_f32_e32 v60, 1.0, v60
	v_rcp_f32_e32 v60, v60
	v_add_f32_e32 v58, 1.0, v58
	v_add_f32_e32 v56, 1.0, v56
	v_rcp_f32_e32 v61, v56
	v_add_f32_e32 v56, v57, v221
	v_mul_f32_e32 v56, 0xbfb8aa3b, v56
	v_exp_f32_e32 v56, v56
	v_rcp_f32_e32 v70, v58
	v_add_f32_e32 v58, v63, v219
	v_mul_f32_e32 v58, 0xbfb8aa3b, v58
	v_add_f32_e32 v56, 1.0, v56
	v_rcp_f32_e32 v69, v56
	v_pk_mul_f32 v[56:57], v[60:61], s[38:39] op_sel_hi:[1,0]
	v_exp_f32_e32 v58, v58
	v_pk_mul_f32 v[60:61], v[224:225], v[56:57]
	v_mul_f32_e32 v62, 0xbfb8aa3b, v62
	v_pk_add_f32 v[72:73], v[60:61], v[60:61]
	v_mul_f32_e32 v56, 0x3fb8aa3b, v60
	v_fmamk_f32 v57, v72, 0x3ab60b61, v195
	v_exp_f32_e32 v56, v56
	v_fmaak_f32 v57, v72, v57, 0x3d2aaaab
	v_exp_f32_e32 v62, v62
	v_fmaak_f32 v57, v72, v57, 0x3e2aaaab
	v_add_f32_e32 v58, 1.0, v58
	v_fma_f32 v57, v72, v57, 0.5
	v_rcp_f32_e32 v63, v58
	v_add_f32_e32 v58, v59, v223
	v_fma_f32 v57, v72, v57, 1.0
	v_mul_f32_e32 v58, 0xbfb8aa3b, v58
	v_mul_f32_e64 v57, v57, -v72
	v_fma_f32 v60, -v56, v56, 1.0
	v_cmp_lt_f32_e64 s[12:13], s84, v72
	v_add_f32_e32 v62, 1.0, v62
	v_exp_f32_e32 v58, v58
	v_cndmask_b32_e64 v57, v60, v57, s[12:13]
	v_rcp_f32_e32 v62, v62
	v_sqrt_f32_e32 v60, v57
	v_mul_f32_e32 v57, 0x3fb8aa3b, v61
	v_fmamk_f32 v61, v73, 0x3ab60b61, v195
	v_fmaak_f32 v61, v73, v61, 0x3d2aaaab
	v_fmaak_f32 v61, v73, v61, 0x3e2aaaab
	v_add_f32_e32 v58, 1.0, v58
	v_fma_f32 v61, v73, v61, 0.5
	v_rcp_f32_e32 v71, v58
	v_pk_mul_f32 v[58:59], v[62:63], s[38:39] op_sel_hi:[1,0]
	v_fma_f32 v61, v73, v61, 1.0
	v_pk_mul_f32 v[62:63], v[226:227], v[58:59]
	v_cmp_lt_f32_e64 s[8:9], s84, v73
	v_mul_f32_e64 v61, v61, -v73
	v_pk_add_f32 v[72:73], v[62:63], v[62:63]
	v_mul_f32_e32 v58, 0x3fb8aa3b, v62
	v_fmamk_f32 v59, v72, 0x3ab60b61, v195
	v_exp_f32_e32 v58, v58
	v_fmaak_f32 v59, v72, v59, 0x3d2aaaab
	v_fmaak_f32 v59, v72, v59, 0x3e2aaaab
	v_fma_f32 v59, v72, v59, 0.5
	v_fma_f32 v59, v72, v59, 1.0
	v_mul_f32_e64 v59, v59, -v72
	v_fma_f32 v62, -v58, v58, 1.0
	v_cmp_lt_f32_e64 s[12:13], s84, v72
	v_exp_f32_e32 v57, v57
	s_nop 0
	v_cndmask_b32_e64 v59, v62, v59, s[12:13]
	v_sqrt_f32_e32 v62, v59
	v_mul_f32_e32 v59, 0x3fb8aa3b, v63
	v_fmamk_f32 v63, v73, 0x3ab60b61, v195
	v_exp_f32_e32 v59, v59
	v_fmaak_f32 v63, v73, v63, 0x3d2aaaab
	v_fmaak_f32 v63, v73, v63, 0x3e2aaaab
	v_fma_f32 v63, v73, v63, 0.5
	v_fma_f32 v67, -v57, v57, 1.0
	v_fma_f32 v63, v73, v63, 1.0
	v_cndmask_b32_e64 v61, v67, v61, s[8:9]
	v_cmp_lt_f32_e64 s[8:9], s84, v73
	v_mul_f32_e64 v63, v63, -v73
	v_fma_f32 v67, -v59, v59, 1.0
	v_cndmask_b32_e64 v63, v67, v63, s[8:9]
	v_sqrt_f32_e32 v61, v61
	v_sqrt_f32_e32 v63, v63
	v_bitop3_b32 v67, v166, v164, 4 bitop3:0x36
	v_lshlrev_b32_e32 v67, 4, v67
	v_pk_mul_f32 v[60:61], v[68:69], v[60:61]
	v_pk_mul_f32 v[62:63], v[70:71], v[62:63]
	v_pk_mul_f32 v[60:61], v[60:61], v[168:169]
	v_pk_mul_f32 v[62:63], v[62:63], v[142:143]
	ds_write_b128 v66, v[56:59] offset:8256
	ds_write_b128 v66, v[60:63] offset:24640
	v_add3_u32 v67, v167, v67, v165
	v_lshl_add_u64 v[56:57], s[2:3], 0, v[64:65]
	s_mov_b64 s[2:3], s[48:49]
	s_waitcnt lgkmcnt(0)
	s_waitcnt vmcnt(3)
	v_add_f32_e32 v52, v52, v228
	v_lshl_add_u64 v[60:61], s[2:3], 0, v[64:65]
	s_mov_b64 s[2:3], s[74:75]
	s_add_u32 s2, s2, s30
	s_addc_u32 s3, s3, 0
	v_lshl_add_u64 v[68:69], s[2:3], 0, v[144:145]
	v_add_co_u32_e64 v68, s[8:9], s37, v68
	v_mul_f32_e32 v52, 0xbfb8aa3b, v52
	s_nop 0
	v_addc_co_u32_e64 v69, s[8:9], 0, v69, s[8:9]
	v_exp_f32_e32 v52, v52
	v_add_f32_e32 v54, v54, v230
	v_mul_f32_e32 v54, 0xbfb8aa3b, v54
	v_exp_f32_e32 v54, v54
	v_add_f32_e32 v52, 1.0, v52
	v_rcp_f32_e32 v52, v52
	ds_read_b64 v[72:73], v67
	v_add_f32_e32 v54, 1.0, v54
	v_rcp_f32_e32 v54, v54
	s_mov_b64 s[2:3], s[44:45]
	s_waitcnt lgkmcnt(0)
	v_lshlrev_b32_e32 v74, 16, v72
	v_and_b32_e32 v75, 0xffff0000, v72
	v_lshlrev_b32_e32 v72, 16, v73
	v_and_b32_e32 v73, 0xffff0000, v73
	v_add_f32_e32 v48, v48, v232
	v_mul_f32_e32 v48, 0xbfb8aa3b, v48
	v_exp_f32_e32 v48, v48
	v_add_f32_e32 v50, v50, v234
	v_mul_f32_e32 v50, 0xbfb8aa3b, v50
	v_exp_f32_e32 v50, v50
	v_add_f32_e32 v48, 1.0, v48
	v_rcp_f32_e32 v56, v48
	v_add_f32_e32 v48, v53, v229
	v_mul_f32_e32 v48, 0xbfb8aa3b, v48
	v_exp_f32_e32 v48, v48
	v_add_f32_e32 v50, 1.0, v50
	v_rcp_f32_e32 v58, v50
	v_add_f32_e32 v50, v55, v231
	v_add_f32_e32 v48, 1.0, v48
	v_rcp_f32_e32 v53, v48
	v_add_f32_e32 v48, v49, v233
	v_mul_f32_e32 v48, 0xbfb8aa3b, v48
	v_exp_f32_e32 v48, v48
	v_mul_f32_e32 v50, 0xbfb8aa3b, v50
	v_exp_f32_e32 v50, v50
	v_add_f32_e32 v48, 1.0, v48
	v_rcp_f32_e32 v57, v48
	v_pk_mul_f32 v[48:49], v[52:53], s[38:39] op_sel_hi:[1,0]
	v_add_f32_e32 v50, 1.0, v50
	v_pk_mul_f32 v[52:53], v[236:237], v[48:49]
	v_rcp_f32_e32 v55, v50
	v_pk_add_f32 v[60:61], v[52:53], v[52:53]
	v_mul_f32_e32 v48, 0x3fb8aa3b, v52
	v_fmamk_f32 v49, v60, 0x3ab60b61, v195
	v_exp_f32_e32 v48, v48
	v_fmaak_f32 v49, v60, v49, 0x3d2aaaab
	v_fmaak_f32 v49, v60, v49, 0x3e2aaaab
	v_fma_f32 v49, v60, v49, 0.5
	v_fma_f32 v49, v60, v49, 1.0
	v_add_f32_e32 v50, v51, v235
	v_mul_f32_e64 v49, v49, -v60
	v_fma_f32 v52, -v48, v48, 1.0
	v_cmp_lt_f32_e64 s[12:13], s84, v60
	v_mul_f32_e32 v50, 0xbfb8aa3b, v50
	v_exp_f32_e32 v50, v50
	v_cndmask_b32_e64 v49, v52, v49, s[12:13]
	v_sqrt_f32_e32 v52, v49
	v_mul_f32_e32 v49, 0x3fb8aa3b, v53
	v_fmamk_f32 v53, v61, 0x3ab60b61, v195
	v_exp_f32_e32 v49, v49
	v_fmaak_f32 v53, v61, v53, 0x3d2aaaab
	v_fmaak_f32 v53, v61, v53, 0x3e2aaaab
	v_fma_f32 v53, v61, v53, 0.5
	v_add_f32_e32 v50, 1.0, v50
	v_fma_f32 v53, v61, v53, 1.0
	v_rcp_f32_e32 v59, v50
	v_pk_mul_f32 v[50:51], v[54:55], s[38:39] op_sel_hi:[1,0]
	v_cmp_lt_f32_e64 s[8:9], s84, v61
	v_mul_f32_e64 v53, v53, -v61
	v_fma_f32 v60, -v49, v49, 1.0
	v_pk_mul_f32 v[54:55], v[238:239], v[50:51]
	v_cndmask_b32_e64 v53, v60, v53, s[8:9]
	v_pk_add_f32 v[60:61], v[54:55], v[54:55]
	v_mul_f32_e32 v50, 0x3fb8aa3b, v54
	v_fmamk_f32 v51, v60, 0x3ab60b61, v195
	v_exp_f32_e32 v50, v50
	v_fmaak_f32 v51, v60, v51, 0x3d2aaaab
	v_fmaak_f32 v51, v60, v51, 0x3e2aaaab
	v_fma_f32 v51, v60, v51, 0.5
	v_fma_f32 v51, v60, v51, 1.0
	v_mul_f32_e64 v51, v51, -v60
	v_fma_f32 v54, -v50, v50, 1.0
	v_cmp_lt_f32_e64 s[12:13], s84, v60
	v_cmp_lt_f32_e64 s[8:9], s84, v61
	v_sqrt_f32_e32 v53, v53
	v_cndmask_b32_e64 v51, v54, v51, s[12:13]
	v_sqrt_f32_e32 v54, v51
	v_mul_f32_e32 v51, 0x3fb8aa3b, v55
	v_fmamk_f32 v55, v61, 0x3ab60b61, v195
	v_exp_f32_e32 v51, v51
	v_fmaak_f32 v55, v61, v55, 0x3d2aaaab
	v_fmaak_f32 v55, v61, v55, 0x3e2aaaab
	v_fma_f32 v55, v61, v55, 0.5
	v_fma_f32 v55, v61, v55, 1.0
	v_mul_f32_e64 v55, v55, -v61
	v_fma_f32 v60, -v51, v51, 1.0
	v_cndmask_b32_e64 v55, v60, v55, s[8:9]
	v_sqrt_f32_e32 v55, v55
	v_pk_mul_f32 v[52:53], v[56:57], v[52:53]
	v_bitop3_b32 v60, v166, v164, 6 bitop3:0x36
	v_pk_mul_f32 v[52:53], v[52:53], v[74:75]
	v_pk_mul_f32 v[54:55], v[58:59], v[54:55]
	v_lshlrev_b32_e32 v60, 4, v60
	v_pk_mul_f32 v[54:55], v[54:55], v[72:73]
	ds_write_b128 v66, v[48:51] offset:8320
	ds_write_b128 v66, v[52:55] offset:24704
	v_add3_u32 v60, v167, v60, v165
	v_lshl_add_u64 v[48:49], s[2:3], 0, v[64:65]
	s_mov_b64 s[2:3], s[48:49]
	s_waitcnt lgkmcnt(0)
	s_waitcnt vmcnt(0)
	v_add_f32_e32 v12, v12, v240
	v_lshl_add_u64 v[52:53], s[2:3], 0, v[64:65]
	s_mov_b64 s[2:3], s[74:75]
	s_add_u32 s2, s2, s30
	s_addc_u32 s3, s3, 0
	v_lshl_add_u64 v[56:57], s[2:3], 0, v[144:145]
	v_add_co_u32_e64 v56, s[8:9], s37, v56
	v_mul_f32_e32 v12, 0xbfb8aa3b, v12
	s_nop 0
	v_addc_co_u32_e64 v57, s[8:9], 0, v57, s[8:9]
	v_exp_f32_e32 v12, v12
	v_add_f32_e32 v14, v14, v242
	v_mul_f32_e32 v14, 0xbfb8aa3b, v14
	v_exp_f32_e32 v14, v14
	v_add_f32_e32 v12, 1.0, v12
	v_rcp_f32_e32 v12, v12
	ds_read_b64 v[60:61], v60
	v_add_f32_e32 v14, 1.0, v14
	v_rcp_f32_e32 v14, v14
	s_waitcnt lgkmcnt(0)
	v_lshlrev_b32_e32 v62, 16, v60
	v_and_b32_e32 v63, 0xffff0000, v60
	v_lshlrev_b32_e32 v60, 16, v61
	v_and_b32_e32 v61, 0xffff0000, v61
	v_add_f32_e32 v8, v8, v244
	v_mul_f32_e32 v8, 0xbfb8aa3b, v8
	v_exp_f32_e32 v8, v8
	v_add_f32_e32 v10, v10, v246
	v_mul_f32_e32 v10, 0xbfb8aa3b, v10
	v_exp_f32_e32 v10, v10
	v_add_f32_e32 v8, 1.0, v8
	v_rcp_f32_e32 v48, v8
	v_add_f32_e32 v8, v13, v241
	v_mul_f32_e32 v8, 0xbfb8aa3b, v8
	v_exp_f32_e32 v8, v8
	v_add_f32_e32 v10, 1.0, v10
	v_rcp_f32_e32 v50, v10
	v_add_f32_e32 v10, v15, v243
	v_add_f32_e32 v8, 1.0, v8
	v_rcp_f32_e32 v13, v8
	v_add_f32_e32 v8, v9, v245
	v_mul_f32_e32 v8, 0xbfb8aa3b, v8
	v_exp_f32_e32 v8, v8
	v_mul_f32_e32 v10, 0xbfb8aa3b, v10
	v_exp_f32_e32 v10, v10
	v_add_f32_e32 v8, 1.0, v8
	v_rcp_f32_e32 v49, v8
	v_pk_mul_f32 v[8:9], v[12:13], s[38:39] op_sel_hi:[1,0]
	v_add_f32_e32 v10, 1.0, v10
	v_pk_mul_f32 v[12:13], v[248:249], v[8:9]
	v_rcp_f32_e32 v15, v10
	v_pk_add_f32 v[52:53], v[12:13], v[12:13]
	v_mul_f32_e32 v8, 0x3fb8aa3b, v12
	v_fmamk_f32 v9, v52, 0x3ab60b61, v195
	v_exp_f32_e32 v8, v8
	v_fmaak_f32 v9, v52, v9, 0x3d2aaaab
	v_fmaak_f32 v9, v52, v9, 0x3e2aaaab
	v_fma_f32 v9, v52, v9, 0.5
	v_fma_f32 v9, v52, v9, 1.0
	v_add_f32_e32 v10, v11, v247
	v_mul_f32_e64 v9, v9, -v52
	v_fma_f32 v12, -v8, v8, 1.0
	v_cmp_lt_f32_e64 s[12:13], s84, v52
	v_mul_f32_e32 v10, 0xbfb8aa3b, v10
	v_exp_f32_e32 v10, v10
	v_cndmask_b32_e64 v9, v12, v9, s[12:13]
	v_sqrt_f32_e32 v12, v9
	v_mul_f32_e32 v9, 0x3fb8aa3b, v13
	v_fmamk_f32 v13, v53, 0x3ab60b61, v195
	v_exp_f32_e32 v9, v9
	v_fmaak_f32 v13, v53, v13, 0x3d2aaaab
	v_fmaak_f32 v13, v53, v13, 0x3e2aaaab
	v_fma_f32 v13, v53, v13, 0.5
	v_add_f32_e32 v10, 1.0, v10
	v_fma_f32 v13, v53, v13, 1.0
	v_rcp_f32_e32 v51, v10
	v_pk_mul_f32 v[10:11], v[14:15], s[38:39] op_sel_hi:[1,0]
	v_cmp_lt_f32_e64 s[8:9], s84, v53
	v_mul_f32_e64 v13, v13, -v53
	v_fma_f32 v52, -v9, v9, 1.0
	v_pk_mul_f32 v[14:15], v[250:251], v[10:11]
	v_cndmask_b32_e64 v13, v52, v13, s[8:9]
	v_pk_add_f32 v[52:53], v[14:15], v[14:15]
	v_mul_f32_e32 v10, 0x3fb8aa3b, v14
	v_fmamk_f32 v11, v52, 0x3ab60b61, v195
	v_exp_f32_e32 v10, v10
	v_fmaak_f32 v11, v52, v11, 0x3d2aaaab
	v_fmaak_f32 v11, v52, v11, 0x3e2aaaab
	v_fma_f32 v11, v52, v11, 0.5
	v_fma_f32 v11, v52, v11, 1.0
	v_mul_f32_e64 v11, v11, -v52
	v_fma_f32 v14, -v10, v10, 1.0
	v_cmp_lt_f32_e64 s[12:13], s84, v52
	v_cmp_lt_f32_e64 s[8:9], s84, v53
	v_sqrt_f32_e32 v13, v13
	v_cndmask_b32_e64 v11, v14, v11, s[12:13]
	v_sqrt_f32_e32 v14, v11
	v_mul_f32_e32 v11, 0x3fb8aa3b, v15
	v_fmamk_f32 v15, v53, 0x3ab60b61, v195
	v_exp_f32_e32 v11, v11
	v_fmaak_f32 v15, v53, v15, 0x3d2aaaab
	v_fmaak_f32 v15, v53, v15, 0x3e2aaaab
	v_fma_f32 v15, v53, v15, 0.5
	v_fma_f32 v15, v53, v15, 1.0
	v_mul_f32_e64 v15, v15, -v53
	v_fma_f32 v52, -v11, v11, 1.0
	v_cndmask_b32_e64 v15, v52, v15, s[8:9]
	v_sqrt_f32_e32 v15, v15
	v_pk_mul_f32 v[12:13], v[48:49], v[12:13]
	v_cmp_gt_i32_e64 s[8:9], 3, v161
	v_pk_mul_f32 v[12:13], v[12:13], v[62:63]
	v_pk_mul_f32 v[14:15], v[50:51], v[14:15]
	s_nop 0
	v_pk_mul_f32 v[14:15], v[14:15], v[60:61]
	ds_write_b128 v66, v[8:11] offset:8384
	ds_write_b128 v66, v[12:15] offset:24768
	v_and_b32_e32 v8, 63, v163
	v_lshlrev_b32_e32 v10, 2, v8
	v_lshl_or_b32 v9, v161, 12, v10
	v_add_u32_e32 v12, s60, v9
	s_waitcnt lgkmcnt(0)
	s_barrier
	ds_read2st64_b32 v[14:15], v12 offset0:46 offset1:47
	ds_read2st64_b32 v[48:49], v12 offset0:110 offset1:111
	ds_read2st64_b32 v[50:51], v12 offset0:44 offset1:45
	ds_read2st64_b32 v[52:53], v12 offset0:108 offset1:109
	v_and_b32_e32 v11, 0x1fffffc0, v162
	s_waitcnt lgkmcnt(2)
	v_fma_f32 v9, 0, v15, v49
	v_fmac_f32_e32 v48, v9, v14
	s_waitcnt lgkmcnt(0)
	v_fma_f32 v9, v48, v51, v53
	ds_read2st64_b32 v[48:49], v12 offset0:42 offset1:43
	ds_read2st64_b32 v[54:55], v12 offset0:106 offset1:107
	v_fmac_f32_e32 v52, v9, v50
	v_mul_f32_e32 v14, v15, v14
	v_mov_b32_e32 v62, v51
	s_waitcnt lgkmcnt(0)
	v_fma_f32 v9, v52, v49, v55
	ds_read2st64_b32 v[52:53], v12 offset0:40 offset1:41
	ds_read2st64_b32 v[56:57], v12 offset0:104 offset1:105
	v_fmac_f32_e32 v54, v9, v48
	s_waitcnt lgkmcnt(1)
	v_mov_b32_e32 v66, v53
	s_waitcnt lgkmcnt(0)
	v_fma_f32 v9, v54, v53, v57
	ds_read2st64_b32 v[54:55], v12 offset0:38 offset1:39
	ds_read2st64_b32 v[58:59], v12 offset0:102 offset1:103
	v_fmac_f32_e32 v56, v9, v52
	v_mul_f32_e32 v9, v14, v51
	v_mov_b32_e32 v68, v53
	s_waitcnt lgkmcnt(1)
	v_mov_b32_e32 v63, v54
	s_waitcnt lgkmcnt(0)
	v_fmac_f32_e32 v59, v56, v55
	ds_read2st64_b32 v[56:57], v12 offset0:36 offset1:37
	ds_read2st64_b32 v[60:61], v12 offset0:100 offset1:101
	v_mov_b32_e32 v15, v59
	v_mov_b32_e32 v51, v58
	v_pk_fma_f32 v[14:15], v[14:15], v[62:63], v[50:51]
	v_mul_f32_e32 v58, v9, v50
	v_mov_b32_e32 v59, v15
	v_mov_b32_e32 v14, v49
	s_waitcnt lgkmcnt(1)
	v_mov_b32_e32 v15, v57
	v_pk_mul_f32 v[50:51], v[58:59], v[14:15]
	s_waitcnt lgkmcnt(0)
	v_mov_b32_e32 v49, v61
	v_pk_mul_f32 v[50:51], v[50:51], v[48:49]
	v_pk_fma_f32 v[14:15], v[58:59], v[14:15], v[48:49]
	ds_read2st64_b32 v[48:49], v12 offset0:34 offset1:35
	ds_read2st64_b32 v[58:59], v12 offset0:98 offset1:99
	ds_read2st64_b32 v[62:63], v12 offset0:32 offset1:33
	ds_read2st64_b32 v[64:65], v12 offset0:96 offset1:97
	v_mov_b32_e32 v14, v50
	v_mov_b32_e32 v69, v56
	v_pk_mul_f32 v[50:51], v[50:51], v[66:67]
	v_mov_b32_e32 v53, v60
	v_pk_mul_f32 v[50:51], v[50:51], v[52:53]
	v_pk_fma_f32 v[14:15], v[14:15], v[68:69], v[52:53]
	v_lshl_add_u32 v9, v8, 3, s60
	v_mov_b32_e32 v51, v15
	v_mov_b32_e32 v14, v55
	s_waitcnt lgkmcnt(3)
	v_mov_b32_e32 v15, v49
	v_pk_mul_f32 v[52:53], v[50:51], v[14:15]
	s_waitcnt lgkmcnt(2)
	v_mov_b32_e32 v55, v59
	v_pk_mul_f32 v[52:53], v[52:53], v[54:55]
	v_pk_fma_f32 v[14:15], v[50:51], v[14:15], v[54:55]
	v_mov_b32_e32 v50, v57
	v_mov_b32_e32 v14, v52
	v_mov_b32_e32 v54, v57
	v_mov_b32_e32 v55, v48
	v_pk_mul_f32 v[50:51], v[52:53], v[50:51]
	v_mov_b32_e32 v57, v58
	v_pk_mul_f32 v[50:51], v[50:51], v[56:57]
	v_pk_fma_f32 v[14:15], v[14:15], v[54:55], v[56:57]
	v_lshl_add_u32 v11, v11, 3, v9
	v_mov_b32_e32 v51, v15
	v_mov_b32_e32 v14, v49
	s_waitcnt lgkmcnt(1)
	v_mov_b32_e32 v15, v63
	v_pk_mul_f32 v[52:53], v[50:51], v[14:15]
	s_waitcnt lgkmcnt(0)
	v_mov_b32_e32 v49, v65
	v_pk_mul_f32 v[52:53], v[52:53], v[48:49]
	v_pk_fma_f32 v[14:15], v[50:51], v[14:15], v[48:49]
	v_mov_b32_e32 v48, v63
	v_mov_b32_e32 v14, v52
	v_mov_b32_e32 v50, v63
	v_mov_b32_e32 v51, v62
	v_pk_mul_f32 v[48:49], v[52:53], v[48:49]
	v_mov_b32_e32 v63, v64
	v_pk_mul_f32 v[48:49], v[48:49], v[62:63]
	v_pk_fma_f32 v[14:15], v[14:15], v[50:51], v[62:63]
	s_nop 0
	v_mov_b32_e32 v49, v15
	ds_write_b64 v11, v[48:49] offset:40960
	v_sub_u32_e32 v11, v9, v10
	s_waitcnt lgkmcnt(0)
	s_barrier
	ds_read_b32 v11, v11 offset:43264
	s_and_saveexec_b64 s[2:3], s[8:9]
	s_cbranch_execz .LBB0_367
	ds_read_b64 v[14:15], v9 offset:42496
	s_waitcnt lgkmcnt(0)
	v_fmac_f32_e32 v15, v11, v14
	v_mov_b32_e32 v11, v15
	s_or_b64 exec, exec, s[2:3]
	v_cmp_gt_i32_e64 s[8:9], 2, v161
	s_and_saveexec_b64 s[2:3], s[8:9]
	s_cbranch_execnz .LBB0_368
